# code placement (sec 9.3): FFN-in, Resid, Proj K-loop heads and the attention step loop head aligned to 64 bytes (on v52)
# baseline (speedup 1.0000x reference)
.LBB0_204:
	s_or_b64 exec, exec, s[6:7]
	s_add_i32 s4, s16, 1
	s_cmp_lg_u32 s16, 2
	s_cselect_b32 s24, s4, 0
	s_mul_i32 s4, s24, 0x4400
	v_add_u32_e32 v162, s4, v175
	s_add_i32 s4, s24, 1
	s_cmp_lg_u32 s24, 2
	s_cselect_b32 s16, s4, 0
	s_add_i32 s15, s15, 2
	s_addk_i32 s13, 0x80
	s_cmp_ge_u32 s17, s12
	s_waitcnt vmcnt(3)
	ds_write_b128 v162, v[144:147]
	s_waitcnt vmcnt(2)
	ds_write_b128 v162, v[148:151] offset:8704
	s_waitcnt vmcnt(1)
	ds_write2_b64 v189, v[156:157], v[158:159] offset0:128 offset1:130
	s_waitcnt vmcnt(0)
	ds_write2_b64 v191, v[152:153], v[154:155] offset1:2
	s_waitcnt lgkmcnt(0)
	s_barrier
	s_cbranch_scc1 .LBB0_220
	.p2align 6

.LBB0_252:
	s_ashr_i32 s19, s18, 31
	s_lshl_b64 s[6:7], s[18:19], 19
	s_add_u32 s84, s0, s6
	s_addc_u32 s85, s1, s7
	s_and_b64 s[6:7], s[38:39], exec
	s_cselect_b32 s4, s85, s43
	s_cselect_b32 s11, s84, s42
	s_ashr_i32 s17, s16, 31
	s_lshl_b64 s[6:7], s[16:17], 19
	s_add_u32 s6, s26, s6
	s_addc_u32 s7, s27, s7
	s_and_b64 s[24:25], s[38:39], exec
	s_cselect_b32 s17, s7, s83
	s_cselect_b32 s19, s6, s82
	s_add_u32 s42, s42, 0x40080
	s_addc_u32 s43, s43, 0
	s_add_u32 s24, s82, 0x100
	s_addc_u32 s25, s83, 0
	s_mov_b32 s41, -2
	s_waitcnt lgkmcnt(0)
	s_add_u32 s22, s42, 0xfffc0080
	s_addc_u32 s23, s43, -1
	s_add_i32 s28, 0, 0x10000
	s_cmp_eq_u32 s41, 12
	s_cselect_b32 vcc_hi, s4, s23
	s_cselect_b32 vcc_lo, s11, s22
	v_add_u32_e32 v160, s28, v167
	s_cselect_b32 s83, s17, s25
	s_cselect_b32 s82, s19, s24
	s_add_i32 s22, 0, 0x14000
	ds_read_b128 v[148:151], v160
	ds_read_b128 v[152:155], v160 offset:1024
	ds_read_b128 v[156:159], v160 offset:2048
	ds_read_b128 v[174:177], v160 offset:3072
	v_add_u32_e32 v160, s22, v167
	ds_read_b128 v[178:181], v160
	ds_read_b128 v[182:185], v160 offset:1024
	ds_read_b128 v[186:189], v160 offset:2048
	ds_read_b128 v[190:193], v160 offset:3072
	v_lshl_add_u64 v[162:163], s[42:43], 0, v[144:145]
	s_add_i32 m0, s81, 0xc000
	ds_read_b128 v[194:197], v173
	ds_read_b128 v[198:201], v173 offset:1024
	ds_read_b128 v[202:205], v173 offset:2048
	ds_read_b128 v[206:209], v173 offset:3072
	ds_read_b128 v[210:213], v173 offset:4096
	ds_read_b128 v[222:225], v173 offset:5120
	ds_read_b128 v[234:237], v173 offset:6144
	ds_read_b128 v[238:241], v173 offset:7168
	global_load_lds_dwordx4 v[162:163], off
	v_lshl_add_u64 v[162:163], s[42:43], 0, v[146:147]
	s_add_i32 m0, s81, 0xe000
	s_nop 0
	global_load_lds_dwordx4 v[162:163], off
	s_waitcnt vmcnt(8)
	s_waitcnt lgkmcnt(0)
	s_barrier
	s_setprio 1
	s_waitcnt lgkmcnt(0)
	v_mfma_f32_16x16x32_bf16 v[124:127], v[148:151], v[194:197], 0
	v_mfma_f32_16x16x32_bf16 v[120:123], v[156:159], v[194:197], 0
	v_mfma_f32_16x16x32_bf16 v[108:111], v[148:151], v[202:205], 0
	v_mfma_f32_16x16x32_bf16 v[104:107], v[156:159], v[202:205], 0
	v_mfma_f32_16x16x32_bf16 v[92:95], v[148:151], v[210:213], 0
	v_mfma_f32_16x16x32_bf16 v[88:91], v[156:159], v[210:213], 0
	v_mfma_f32_16x16x32_bf16 v[76:79], v[148:151], v[234:237], 0
	v_mfma_f32_16x16x32_bf16 v[72:75], v[156:159], v[234:237], 0
	v_mfma_f32_16x16x32_bf16 v[124:127], v[152:155], v[198:201], v[124:127]
	v_mfma_f32_16x16x32_bf16 v[120:123], v[174:177], v[198:201], v[120:123]
	v_mfma_f32_16x16x32_bf16 v[108:111], v[152:155], v[206:209], v[108:111]
	v_mfma_f32_16x16x32_bf16 v[104:107], v[174:177], v[206:209], v[104:107]
	v_mfma_f32_16x16x32_bf16 v[92:95], v[152:155], v[222:225], v[92:95]
	v_mfma_f32_16x16x32_bf16 v[88:91], v[174:177], v[222:225], v[88:91]
	v_mfma_f32_16x16x32_bf16 v[76:79], v[152:155], v[238:241], v[76:79]
	v_mfma_f32_16x16x32_bf16 v[72:75], v[174:177], v[238:241], v[72:75]
	v_mfma_f32_16x16x32_bf16 v[116:119], v[178:181], v[194:197], 0
	v_mfma_f32_16x16x32_bf16 v[112:115], v[186:189], v[194:197], 0
	v_mfma_f32_16x16x32_bf16 v[100:103], v[178:181], v[202:205], 0
	v_mfma_f32_16x16x32_bf16 v[96:99], v[186:189], v[202:205], 0
	v_mfma_f32_16x16x32_bf16 v[84:87], v[178:181], v[210:213], 0
	v_mfma_f32_16x16x32_bf16 v[80:83], v[186:189], v[210:213], 0
	v_mfma_f32_16x16x32_bf16 v[68:71], v[178:181], v[234:237], 0
	v_mfma_f32_16x16x32_bf16 v[64:67], v[186:189], v[234:237], 0
	v_mfma_f32_16x16x32_bf16 v[116:119], v[182:185], v[198:201], v[116:119]
	v_mfma_f32_16x16x32_bf16 v[112:115], v[190:193], v[198:201], v[112:115]
	v_mfma_f32_16x16x32_bf16 v[100:103], v[182:185], v[206:209], v[100:103]
	v_mfma_f32_16x16x32_bf16 v[96:99], v[190:193], v[206:209], v[96:99]
	v_mfma_f32_16x16x32_bf16 v[84:87], v[182:185], v[222:225], v[84:87]
	v_mfma_f32_16x16x32_bf16 v[80:83], v[190:193], v[222:225], v[80:83]
	v_mfma_f32_16x16x32_bf16 v[68:71], v[182:185], v[238:241], v[68:71]
	v_mfma_f32_16x16x32_bf16 v[64:67], v[190:193], v[238:241], v[64:67]
	s_setprio 0
	s_barrier
	s_add_i32 s23, s28, s80
	v_lshl_add_u64 v[162:163], s[82:83], 0, v[130:131]
	s_mov_b32 m0, s23
	ds_read_b128 v[194:197], v173 offset:16384
	ds_read_b128 v[198:201], v173 offset:17408
	ds_read_b128 v[202:205], v173 offset:18432
	ds_read_b128 v[206:209], v173 offset:19456
	ds_read_b128 v[210:213], v173 offset:20480
	ds_read_b128 v[222:225], v173 offset:21504
	ds_read_b128 v[234:237], v173 offset:22528
	ds_read_b128 v[238:241], v173 offset:23552
	global_load_lds_dwordx4 v[162:163], off
	s_add_i32 m0, s23, 0x2000
	s_add_u32 s50, s82, 0x40000
	v_lshl_add_u64 v[164:165], s[82:83], 0, v[134:135]
	s_addc_u32 s51, s83, 0
	s_add_i32 s22, s22, s80
	global_load_lds_dwordx4 v[164:165], off
	v_lshl_add_u64 v[170:171], s[50:51], 0, v[130:131]
	s_mov_b32 m0, s22
	v_lshl_add_u64 v[214:215], vcc, 0, v[132:133]
	global_load_lds_dwordx4 v[170:171], off
	v_lshl_add_u64 v[170:171], s[50:51], 0, v[134:135]
	s_add_i32 m0, s22, 0x2000
	s_nop 0
	global_load_lds_dwordx4 v[170:171], off
	v_lshl_add_u64 v[170:171], vcc, 0, v[128:129]
	s_mov_b32 m0, s81
	s_nop 0
	global_load_lds_dwordx4 v[170:171], off
	s_mov_b32 m0, s86
	s_nop 0
	global_load_lds_dwordx4 v[214:215], off
	s_waitcnt vmcnt(8)
	s_waitcnt lgkmcnt(0)
	s_barrier
	s_setprio 1
	s_waitcnt lgkmcnt(0)
	v_mfma_f32_16x16x32_bf16 v[60:63], v[148:151], v[194:197], 0
	v_mfma_f32_16x16x32_bf16 v[56:59], v[156:159], v[194:197], 0
	v_mfma_f32_16x16x32_bf16 v[44:47], v[148:151], v[202:205], 0
	v_mfma_f32_16x16x32_bf16 v[40:43], v[156:159], v[202:205], 0
	v_mfma_f32_16x16x32_bf16 v[28:31], v[148:151], v[210:213], 0
	v_mfma_f32_16x16x32_bf16 v[24:27], v[156:159], v[210:213], 0
	v_mfma_f32_16x16x32_bf16 v[12:15], v[148:151], v[234:237], 0
	v_mfma_f32_16x16x32_bf16 v[8:11], v[156:159], v[234:237], 0
	v_mfma_f32_16x16x32_bf16 v[60:63], v[152:155], v[198:201], v[60:63]
	v_mfma_f32_16x16x32_bf16 v[56:59], v[174:177], v[198:201], v[56:59]
	v_mfma_f32_16x16x32_bf16 v[44:47], v[152:155], v[206:209], v[44:47]
	v_mfma_f32_16x16x32_bf16 v[40:43], v[174:177], v[206:209], v[40:43]
	v_mfma_f32_16x16x32_bf16 v[28:31], v[152:155], v[222:225], v[28:31]
	v_mfma_f32_16x16x32_bf16 v[24:27], v[174:177], v[222:225], v[24:27]
	v_mfma_f32_16x16x32_bf16 v[12:15], v[152:155], v[238:241], v[12:15]
	v_mfma_f32_16x16x32_bf16 v[8:11], v[174:177], v[238:241], v[8:11]
	v_mfma_f32_16x16x32_bf16 v[52:55], v[178:181], v[194:197], 0
	v_mfma_f32_16x16x32_bf16 v[48:51], v[186:189], v[194:197], 0
	v_mfma_f32_16x16x32_bf16 v[36:39], v[178:181], v[202:205], 0
	v_mfma_f32_16x16x32_bf16 v[32:35], v[186:189], v[202:205], 0
	v_mfma_f32_16x16x32_bf16 v[20:23], v[178:181], v[210:213], 0
	v_mfma_f32_16x16x32_bf16 v[16:19], v[186:189], v[210:213], 0
	v_mfma_f32_16x16x32_bf16 v[4:7], v[178:181], v[234:237], 0
	v_mfma_f32_16x16x32_bf16 v[0:3], v[186:189], v[234:237], 0
	v_mfma_f32_16x16x32_bf16 v[52:55], v[182:185], v[198:201], v[52:55]
	v_mfma_f32_16x16x32_bf16 v[48:51], v[190:193], v[198:201], v[48:51]
	v_mfma_f32_16x16x32_bf16 v[36:39], v[182:185], v[206:209], v[36:39]
	v_mfma_f32_16x16x32_bf16 v[32:35], v[190:193], v[206:209], v[32:35]
	v_mfma_f32_16x16x32_bf16 v[20:23], v[182:185], v[222:225], v[20:23]
	v_mfma_f32_16x16x32_bf16 v[16:19], v[190:193], v[222:225], v[16:19]
	v_mfma_f32_16x16x32_bf16 v[4:7], v[182:185], v[238:241], v[4:7]
	v_mfma_f32_16x16x32_bf16 v[0:3], v[190:193], v[238:241], v[0:3]
	s_setprio 0
	s_barrier
	s_add_i32 s22, 0, 0x18000
	v_add_u32_e32 v160, s22, v167
	s_add_i32 s23, 0, 0x1c000
	ds_read_b128 v[148:151], v160
	ds_read_b128 v[152:155], v160 offset:1024
	ds_read_b128 v[156:159], v160 offset:2048
	ds_read_b128 v[174:177], v160 offset:3072
	v_add_u32_e32 v160, s23, v167
	ds_read_b128 v[178:181], v160
	ds_read_b128 v[182:185], v160 offset:1024
	ds_read_b128 v[186:189], v160 offset:2048
	ds_read_b128 v[190:193], v160 offset:3072
	s_add_u32 s50, vcc_lo, 0x40000
	s_addc_u32 s51, vcc_hi, 0
	s_mov_b32 m0, s87
	v_lshl_add_u64 v[226:227], s[50:51], 0, v[128:129]
	ds_read_b128 v[194:197], v173 offset:32768
	ds_read_b128 v[198:201], v173 offset:33792
	ds_read_b128 v[202:205], v173 offset:34816
	ds_read_b128 v[206:209], v173 offset:35840
	ds_read_b128 v[210:213], v173 offset:36864
	ds_read_b128 v[222:225], v173 offset:37888
	ds_read_b128 v[234:237], v173 offset:38912
	ds_read_b128 v[238:241], v173 offset:39936
	global_load_lds_dwordx4 v[226:227], off
	v_lshl_add_u64 v[226:227], s[50:51], 0, v[132:133]
	s_mov_b32 m0, s88
	s_nop 0
	global_load_lds_dwordx4 v[226:227], off
	s_waitcnt vmcnt(8)
	s_waitcnt lgkmcnt(0)
	s_barrier
	s_setprio 1
	s_waitcnt lgkmcnt(0)
	v_mfma_f32_16x16x32_bf16 v[124:127], v[148:151], v[194:197], v[124:127]
	v_mfma_f32_16x16x32_bf16 v[120:123], v[156:159], v[194:197], v[120:123]
	v_mfma_f32_16x16x32_bf16 v[108:111], v[148:151], v[202:205], v[108:111]
	v_mfma_f32_16x16x32_bf16 v[104:107], v[156:159], v[202:205], v[104:107]
	v_mfma_f32_16x16x32_bf16 v[92:95], v[148:151], v[210:213], v[92:95]
	v_mfma_f32_16x16x32_bf16 v[88:91], v[156:159], v[210:213], v[88:91]
	v_mfma_f32_16x16x32_bf16 v[76:79], v[148:151], v[234:237], v[76:79]
	v_mfma_f32_16x16x32_bf16 v[72:75], v[156:159], v[234:237], v[72:75]
	v_mfma_f32_16x16x32_bf16 v[124:127], v[152:155], v[198:201], v[124:127]
	v_mfma_f32_16x16x32_bf16 v[120:123], v[174:177], v[198:201], v[120:123]
	v_mfma_f32_16x16x32_bf16 v[108:111], v[152:155], v[206:209], v[108:111]
	v_mfma_f32_16x16x32_bf16 v[104:107], v[174:177], v[206:209], v[104:107]
	v_mfma_f32_16x16x32_bf16 v[92:95], v[152:155], v[222:225], v[92:95]
	v_mfma_f32_16x16x32_bf16 v[88:91], v[174:177], v[222:225], v[88:91]
	v_mfma_f32_16x16x32_bf16 v[76:79], v[152:155], v[238:241], v[76:79]
	v_mfma_f32_16x16x32_bf16 v[72:75], v[174:177], v[238:241], v[72:75]
	v_mfma_f32_16x16x32_bf16 v[116:119], v[178:181], v[194:197], v[116:119]
	v_mfma_f32_16x16x32_bf16 v[112:115], v[186:189], v[194:197], v[112:115]
	v_mfma_f32_16x16x32_bf16 v[100:103], v[178:181], v[202:205], v[100:103]
	v_mfma_f32_16x16x32_bf16 v[96:99], v[186:189], v[202:205], v[96:99]
	v_mfma_f32_16x16x32_bf16 v[84:87], v[178:181], v[210:213], v[84:87]
	v_mfma_f32_16x16x32_bf16 v[80:83], v[186:189], v[210:213], v[80:83]
	v_mfma_f32_16x16x32_bf16 v[68:71], v[178:181], v[234:237], v[68:71]
	v_mfma_f32_16x16x32_bf16 v[64:67], v[186:189], v[234:237], v[64:67]
	v_mfma_f32_16x16x32_bf16 v[116:119], v[182:185], v[198:201], v[116:119]
	v_mfma_f32_16x16x32_bf16 v[112:115], v[190:193], v[198:201], v[112:115]
	v_mfma_f32_16x16x32_bf16 v[100:103], v[182:185], v[206:209], v[100:103]
	v_mfma_f32_16x16x32_bf16 v[96:99], v[190:193], v[206:209], v[96:99]
	v_mfma_f32_16x16x32_bf16 v[84:87], v[182:185], v[222:225], v[84:87]
	v_mfma_f32_16x16x32_bf16 v[80:83], v[190:193], v[222:225], v[80:83]
	v_mfma_f32_16x16x32_bf16 v[68:71], v[182:185], v[238:241], v[68:71]
	v_mfma_f32_16x16x32_bf16 v[64:67], v[190:193], v[238:241], v[64:67]
	s_setprio 0
	s_barrier
	s_add_i32 s22, s22, s80
	v_lshl_add_u64 v[162:163], v[162:163], 0, s[48:49]
	s_mov_b32 m0, s22
	ds_read_b128 v[194:197], v173 offset:49152
	ds_read_b128 v[198:201], v173 offset:50176
	ds_read_b128 v[202:205], v173 offset:51200
	ds_read_b128 v[206:209], v173 offset:52224
	ds_read_b128 v[210:213], v173 offset:53248
	ds_read_b128 v[222:225], v173 offset:54272
	ds_read_b128 v[234:237], v173 offset:55296
	ds_read_b128 v[238:241], v173 offset:56320
	global_load_lds_dwordx4 v[162:163], off
	s_add_i32 m0, s22, 0x2000
	s_add_u32 s50, s82, 0x40080
	v_lshl_add_u64 v[162:163], v[164:165], 0, s[48:49]
	s_addc_u32 s51, s83, 0
	s_add_i32 s22, s23, s80
	global_load_lds_dwordx4 v[162:163], off
	v_lshl_add_u64 v[162:163], s[50:51], 0, v[130:131]
	s_mov_b32 m0, s22
	s_nop 0
	global_load_lds_dwordx4 v[162:163], off
	v_lshl_add_u64 v[162:163], s[50:51], 0, v[134:135]
	s_add_i32 m0, s22, 0x2000
	s_nop 0
	global_load_lds_dwordx4 v[162:163], off
	v_lshl_add_u64 v[162:163], v[170:171], 0, s[48:49]
	s_mov_b32 m0, s90
	s_nop 0
	global_load_lds_dwordx4 v[162:163], off
	v_lshl_add_u64 v[162:163], v[214:215], 0, s[48:49]
	s_mov_b32 m0, s91
	s_nop 0
	global_load_lds_dwordx4 v[162:163], off
	s_waitcnt vmcnt(8)
	s_waitcnt lgkmcnt(0)
	s_barrier
	s_setprio 1
	s_waitcnt lgkmcnt(0)
	v_mfma_f32_16x16x32_bf16 v[60:63], v[148:151], v[194:197], v[60:63]
	v_mfma_f32_16x16x32_bf16 v[56:59], v[156:159], v[194:197], v[56:59]
	v_mfma_f32_16x16x32_bf16 v[44:47], v[148:151], v[202:205], v[44:47]
	v_mfma_f32_16x16x32_bf16 v[40:43], v[156:159], v[202:205], v[40:43]
	v_mfma_f32_16x16x32_bf16 v[28:31], v[148:151], v[210:213], v[28:31]
	v_mfma_f32_16x16x32_bf16 v[24:27], v[156:159], v[210:213], v[24:27]
	v_mfma_f32_16x16x32_bf16 v[12:15], v[148:151], v[234:237], v[12:15]
	v_mfma_f32_16x16x32_bf16 v[8:11], v[156:159], v[234:237], v[8:11]
	v_mfma_f32_16x16x32_bf16 v[60:63], v[152:155], v[198:201], v[60:63]
	v_mfma_f32_16x16x32_bf16 v[56:59], v[174:177], v[198:201], v[56:59]
	v_mfma_f32_16x16x32_bf16 v[44:47], v[152:155], v[206:209], v[44:47]
	v_mfma_f32_16x16x32_bf16 v[40:43], v[174:177], v[206:209], v[40:43]
	v_mfma_f32_16x16x32_bf16 v[28:31], v[152:155], v[222:225], v[28:31]
	v_mfma_f32_16x16x32_bf16 v[24:27], v[174:177], v[222:225], v[24:27]
	v_mfma_f32_16x16x32_bf16 v[12:15], v[152:155], v[238:241], v[12:15]
	v_mfma_f32_16x16x32_bf16 v[8:11], v[174:177], v[238:241], v[8:11]
	v_mfma_f32_16x16x32_bf16 v[52:55], v[178:181], v[194:197], v[52:55]
	v_mfma_f32_16x16x32_bf16 v[48:51], v[186:189], v[194:197], v[48:51]
	v_mfma_f32_16x16x32_bf16 v[36:39], v[178:181], v[202:205], v[36:39]
	v_mfma_f32_16x16x32_bf16 v[32:35], v[186:189], v[202:205], v[32:35]
	v_mfma_f32_16x16x32_bf16 v[20:23], v[178:181], v[210:213], v[20:23]
	v_mfma_f32_16x16x32_bf16 v[16:19], v[186:189], v[210:213], v[16:19]
	v_mfma_f32_16x16x32_bf16 v[4:7], v[178:181], v[234:237], v[4:7]
	v_mfma_f32_16x16x32_bf16 v[0:3], v[186:189], v[234:237], v[0:3]
	v_mfma_f32_16x16x32_bf16 v[52:55], v[182:185], v[198:201], v[52:55]
	v_mfma_f32_16x16x32_bf16 v[48:51], v[190:193], v[198:201], v[48:51]
	v_mfma_f32_16x16x32_bf16 v[36:39], v[182:185], v[206:209], v[36:39]
	v_mfma_f32_16x16x32_bf16 v[32:35], v[190:193], v[206:209], v[32:35]
	v_mfma_f32_16x16x32_bf16 v[20:23], v[182:185], v[222:225], v[20:23]
	v_mfma_f32_16x16x32_bf16 v[16:19], v[190:193], v[222:225], v[16:19]
	v_mfma_f32_16x16x32_bf16 v[4:7], v[182:185], v[238:241], v[4:7]
	v_mfma_f32_16x16x32_bf16 v[0:3], v[190:193], v[238:241], v[0:3]
	s_setprio 0
	s_barrier
	s_add_i32 s41, s41, 2
	s_add_u32 s42, s42, 0x100
	s_addc_u32 s43, s43, 0
	s_add_u32 s24, s24, 0x100
	s_addc_u32 s25, s25, 0
	s_cmp_gt_u32 s41, 13
	.p2align 6

.LBB0_377:
	s_add_u32 s40, s82, 0x80
	s_addc_u32 s41, s83, 0
	s_add_u32 s4, s84, 0x100
	s_addc_u32 s84, s85, 0
	s_mov_b32 s82, 0
	s_add_i32 s85, s82, 2
	s_add_u32 vcc_lo, s40, 0x80
	s_addc_u32 s83, s41, 0
	s_add_i32 s28, 0, 0x10000
	s_cmp_eq_u32 s95, s82
	s_cselect_b32 s83, s19, s83
	s_cselect_b32 s82, s18, vcc_lo
	s_cselect_b32 vcc_hi, s43, s84
	s_cselect_b32 vcc_lo, s42, s4
	s_add_i32 s22, 0, 0x14000
	v_add_u32_e32 v140, s28, v169
	v_add_u32_e32 v162, s22, v169
	ds_read_b128 v[128:131], v140
	ds_read_b128 v[132:135], v140 offset:1024
	ds_read_b128 v[136:139], v140 offset:2048
	ds_read_b128 v[140:143], v140 offset:3072
	ds_read_b128 v[144:147], v162
	ds_read_b128 v[148:151], v162 offset:1024
	ds_read_b128 v[152:155], v162 offset:2048
	ds_read_b128 v[180:183], v162 offset:3072
	v_lshl_add_u64 v[162:163], s[40:41], 0, v[176:177]
	s_add_i32 m0, s86, 0xc000
	ds_read_b128 v[184:187], v205
	ds_read_b128 v[188:191], v205 offset:1024
	ds_read_b128 v[192:195], v205 offset:2048
	ds_read_b128 v[196:199], v205 offset:3072
	ds_read_b128 v[206:209], v205 offset:4096
	ds_read_b128 v[210:213], v205 offset:5120
	ds_read_b128 v[222:225], v205 offset:6144
	ds_read_b128 v[234:237], v205 offset:7168
	global_load_lds_dwordx4 v[162:163], off
	v_lshl_add_u64 v[162:163], s[40:41], 0, v[178:179]
	s_add_i32 m0, s86, 0xe000
	s_nop 0
	global_load_lds_dwordx4 v[162:163], off
	s_waitcnt vmcnt(8)
	s_waitcnt lgkmcnt(0)
	s_barrier
	s_setprio 1
	s_waitcnt lgkmcnt(0)
	v_mfma_f32_16x16x32_bf16 v[124:127], v[128:131], v[184:187], 0
	v_mfma_f32_16x16x32_bf16 v[120:123], v[136:139], v[184:187], 0
	v_mfma_f32_16x16x32_bf16 v[108:111], v[128:131], v[192:195], 0
	v_mfma_f32_16x16x32_bf16 v[104:107], v[136:139], v[192:195], 0
	v_mfma_f32_16x16x32_bf16 v[92:95], v[128:131], v[206:209], 0
	v_mfma_f32_16x16x32_bf16 v[88:91], v[136:139], v[206:209], 0
	v_mfma_f32_16x16x32_bf16 v[76:79], v[128:131], v[222:225], 0
	v_mfma_f32_16x16x32_bf16 v[72:75], v[136:139], v[222:225], 0
	v_mfma_f32_16x16x32_bf16 v[124:127], v[132:135], v[188:191], v[124:127]
	v_mfma_f32_16x16x32_bf16 v[120:123], v[140:143], v[188:191], v[120:123]
	v_mfma_f32_16x16x32_bf16 v[108:111], v[132:135], v[196:199], v[108:111]
	v_mfma_f32_16x16x32_bf16 v[104:107], v[140:143], v[196:199], v[104:107]
	v_mfma_f32_16x16x32_bf16 v[92:95], v[132:135], v[210:213], v[92:95]
	v_mfma_f32_16x16x32_bf16 v[88:91], v[140:143], v[210:213], v[88:91]
	v_mfma_f32_16x16x32_bf16 v[76:79], v[132:135], v[234:237], v[76:79]
	v_mfma_f32_16x16x32_bf16 v[72:75], v[140:143], v[234:237], v[72:75]
	v_mfma_f32_16x16x32_bf16 v[116:119], v[144:147], v[184:187], 0
	v_mfma_f32_16x16x32_bf16 v[112:115], v[152:155], v[184:187], 0
	v_mfma_f32_16x16x32_bf16 v[100:103], v[144:147], v[192:195], 0
	v_mfma_f32_16x16x32_bf16 v[96:99], v[152:155], v[192:195], 0
	v_mfma_f32_16x16x32_bf16 v[84:87], v[144:147], v[206:209], 0
	v_mfma_f32_16x16x32_bf16 v[80:83], v[152:155], v[206:209], 0
	v_mfma_f32_16x16x32_bf16 v[68:71], v[144:147], v[222:225], 0
	v_mfma_f32_16x16x32_bf16 v[64:67], v[152:155], v[222:225], 0
	v_mfma_f32_16x16x32_bf16 v[116:119], v[148:151], v[188:191], v[116:119]
	v_mfma_f32_16x16x32_bf16 v[112:115], v[180:183], v[188:191], v[112:115]
	v_mfma_f32_16x16x32_bf16 v[100:103], v[148:151], v[196:199], v[100:103]
	v_mfma_f32_16x16x32_bf16 v[96:99], v[180:183], v[196:199], v[96:99]
	v_mfma_f32_16x16x32_bf16 v[84:87], v[148:151], v[210:213], v[84:87]
	v_mfma_f32_16x16x32_bf16 v[80:83], v[180:183], v[210:213], v[80:83]
	v_mfma_f32_16x16x32_bf16 v[68:71], v[148:151], v[234:237], v[68:71]
	v_mfma_f32_16x16x32_bf16 v[64:67], v[180:183], v[234:237], v[64:67]
	s_setprio 0
	s_barrier
	s_add_i32 s23, s28, s81
	v_lshl_add_u64 v[162:163], vcc, 0, v[160:161]
	s_mov_b32 m0, s23
	ds_read_b128 v[184:187], v205 offset:16384
	ds_read_b128 v[188:191], v205 offset:17408
	ds_read_b128 v[192:195], v205 offset:18432
	ds_read_b128 v[196:199], v205 offset:19456
	ds_read_b128 v[206:209], v205 offset:20480
	ds_read_b128 v[210:213], v205 offset:21504
	ds_read_b128 v[222:225], v205 offset:22528
	ds_read_b128 v[234:237], v205 offset:23552
	global_load_lds_dwordx4 v[162:163], off
	s_add_i32 m0, s23, 0x2000
	v_lshl_add_u64 v[164:165], vcc, 0, v[170:171]
	s_add_u32 vcc_lo, vcc_lo, s8
	s_addc_u32 vcc_hi, vcc_hi, 0
	s_add_i32 s22, s22, s81
	global_load_lds_dwordx4 v[164:165], off
	v_lshl_add_u64 v[200:201], vcc, 0, v[160:161]
	s_mov_b32 m0, s22
	v_lshl_add_u64 v[214:215], vcc, 0, v[170:171]
	global_load_lds_dwordx4 v[200:201], off
	s_add_i32 m0, s22, 0x2000
	v_lshl_add_u64 v[226:227], s[82:83], 0, v[156:157]
	global_load_lds_dwordx4 v[214:215], off
	s_mov_b32 m0, s86
	v_lshl_add_u64 v[238:239], s[82:83], 0, v[158:159]
	global_load_lds_dwordx4 v[226:227], off
	s_mov_b32 m0, s87
	s_nop 0
	global_load_lds_dwordx4 v[238:239], off
	s_waitcnt vmcnt(8)
	s_waitcnt lgkmcnt(0)
	s_barrier
	s_setprio 1
	s_waitcnt lgkmcnt(0)
	v_mfma_f32_16x16x32_bf16 v[60:63], v[128:131], v[184:187], 0
	v_mfma_f32_16x16x32_bf16 v[56:59], v[136:139], v[184:187], 0
	v_mfma_f32_16x16x32_bf16 v[44:47], v[128:131], v[192:195], 0
	v_mfma_f32_16x16x32_bf16 v[40:43], v[136:139], v[192:195], 0
	v_mfma_f32_16x16x32_bf16 v[28:31], v[128:131], v[206:209], 0
	v_mfma_f32_16x16x32_bf16 v[24:27], v[136:139], v[206:209], 0
	v_mfma_f32_16x16x32_bf16 v[12:15], v[128:131], v[222:225], 0
	v_mfma_f32_16x16x32_bf16 v[8:11], v[136:139], v[222:225], 0
	v_mfma_f32_16x16x32_bf16 v[60:63], v[132:135], v[188:191], v[60:63]
	v_mfma_f32_16x16x32_bf16 v[56:59], v[140:143], v[188:191], v[56:59]
	v_mfma_f32_16x16x32_bf16 v[44:47], v[132:135], v[196:199], v[44:47]
	v_mfma_f32_16x16x32_bf16 v[40:43], v[140:143], v[196:199], v[40:43]
	v_mfma_f32_16x16x32_bf16 v[28:31], v[132:135], v[210:213], v[28:31]
	v_mfma_f32_16x16x32_bf16 v[24:27], v[140:143], v[210:213], v[24:27]
	v_mfma_f32_16x16x32_bf16 v[12:15], v[132:135], v[234:237], v[12:15]
	v_mfma_f32_16x16x32_bf16 v[8:11], v[140:143], v[234:237], v[8:11]
	v_mfma_f32_16x16x32_bf16 v[52:55], v[144:147], v[184:187], 0
	v_mfma_f32_16x16x32_bf16 v[48:51], v[152:155], v[184:187], 0
	v_mfma_f32_16x16x32_bf16 v[36:39], v[144:147], v[192:195], 0
	v_mfma_f32_16x16x32_bf16 v[32:35], v[152:155], v[192:195], 0
	v_mfma_f32_16x16x32_bf16 v[20:23], v[144:147], v[206:209], 0
	v_mfma_f32_16x16x32_bf16 v[16:19], v[152:155], v[206:209], 0
	v_mfma_f32_16x16x32_bf16 v[4:7], v[144:147], v[222:225], 0
	v_mfma_f32_16x16x32_bf16 v[0:3], v[152:155], v[222:225], 0
	v_mfma_f32_16x16x32_bf16 v[52:55], v[148:151], v[188:191], v[52:55]
	v_mfma_f32_16x16x32_bf16 v[48:51], v[180:183], v[188:191], v[48:51]
	v_mfma_f32_16x16x32_bf16 v[36:39], v[148:151], v[196:199], v[36:39]
	v_mfma_f32_16x16x32_bf16 v[32:35], v[180:183], v[196:199], v[32:35]
	v_mfma_f32_16x16x32_bf16 v[20:23], v[148:151], v[210:213], v[20:23]
	v_mfma_f32_16x16x32_bf16 v[16:19], v[180:183], v[210:213], v[16:19]
	v_mfma_f32_16x16x32_bf16 v[4:7], v[148:151], v[234:237], v[4:7]
	v_mfma_f32_16x16x32_bf16 v[0:3], v[180:183], v[234:237], v[0:3]
	s_setprio 0
	s_barrier
	s_add_i32 s22, 0, 0x18000
	s_add_i32 s23, 0, 0x1c000
	v_add_u32_e32 v140, s22, v169
	v_add_u32_e32 v173, s23, v169
	ds_read_b128 v[128:131], v140
	ds_read_b128 v[132:135], v140 offset:1024
	ds_read_b128 v[136:139], v140 offset:2048
	ds_read_b128 v[140:143], v140 offset:3072
	ds_read_b128 v[144:147], v173
	ds_read_b128 v[148:151], v173 offset:1024
	ds_read_b128 v[152:155], v173 offset:2048
	ds_read_b128 v[180:183], v173 offset:3072
	s_add_u32 s82, s82, s8
	s_addc_u32 s83, s83, 0
	s_mov_b32 m0, s88
	v_lshl_add_u64 v[240:241], s[82:83], 0, v[156:157]
	ds_read_b128 v[184:187], v205 offset:32768
	ds_read_b128 v[188:191], v205 offset:33792
	ds_read_b128 v[192:195], v205 offset:34816
	ds_read_b128 v[196:199], v205 offset:35840
	ds_read_b128 v[206:209], v205 offset:36864
	ds_read_b128 v[210:213], v205 offset:37888
	ds_read_b128 v[222:225], v205 offset:38912
	ds_read_b128 v[234:237], v205 offset:39936
	global_load_lds_dwordx4 v[240:241], off
	v_lshl_add_u64 v[240:241], s[82:83], 0, v[158:159]
	s_mov_b32 m0, s89
	s_nop 0
	global_load_lds_dwordx4 v[240:241], off
	s_waitcnt vmcnt(8)
	s_waitcnt lgkmcnt(0)
	s_barrier
	s_setprio 1
	s_waitcnt lgkmcnt(0)
	v_mfma_f32_16x16x32_bf16 v[124:127], v[128:131], v[184:187], v[124:127]
	v_mfma_f32_16x16x32_bf16 v[120:123], v[136:139], v[184:187], v[120:123]
	v_mfma_f32_16x16x32_bf16 v[108:111], v[128:131], v[192:195], v[108:111]
	v_mfma_f32_16x16x32_bf16 v[104:107], v[136:139], v[192:195], v[104:107]
	v_mfma_f32_16x16x32_bf16 v[92:95], v[128:131], v[206:209], v[92:95]
	v_mfma_f32_16x16x32_bf16 v[88:91], v[136:139], v[206:209], v[88:91]
	v_mfma_f32_16x16x32_bf16 v[76:79], v[128:131], v[222:225], v[76:79]
	v_mfma_f32_16x16x32_bf16 v[72:75], v[136:139], v[222:225], v[72:75]
	v_mfma_f32_16x16x32_bf16 v[124:127], v[132:135], v[188:191], v[124:127]
	v_mfma_f32_16x16x32_bf16 v[120:123], v[140:143], v[188:191], v[120:123]
	v_mfma_f32_16x16x32_bf16 v[108:111], v[132:135], v[196:199], v[108:111]
	v_mfma_f32_16x16x32_bf16 v[104:107], v[140:143], v[196:199], v[104:107]
	v_mfma_f32_16x16x32_bf16 v[92:95], v[132:135], v[210:213], v[92:95]
	v_mfma_f32_16x16x32_bf16 v[88:91], v[140:143], v[210:213], v[88:91]
	v_mfma_f32_16x16x32_bf16 v[76:79], v[132:135], v[234:237], v[76:79]
	v_mfma_f32_16x16x32_bf16 v[72:75], v[140:143], v[234:237], v[72:75]
	v_mfma_f32_16x16x32_bf16 v[116:119], v[144:147], v[184:187], v[116:119]
	v_mfma_f32_16x16x32_bf16 v[112:115], v[152:155], v[184:187], v[112:115]
	v_mfma_f32_16x16x32_bf16 v[100:103], v[144:147], v[192:195], v[100:103]
	v_mfma_f32_16x16x32_bf16 v[96:99], v[152:155], v[192:195], v[96:99]
	v_mfma_f32_16x16x32_bf16 v[84:87], v[144:147], v[206:209], v[84:87]
	v_mfma_f32_16x16x32_bf16 v[80:83], v[152:155], v[206:209], v[80:83]
	v_mfma_f32_16x16x32_bf16 v[68:71], v[144:147], v[222:225], v[68:71]
	v_mfma_f32_16x16x32_bf16 v[64:67], v[152:155], v[222:225], v[64:67]
	v_mfma_f32_16x16x32_bf16 v[116:119], v[148:151], v[188:191], v[116:119]
	v_mfma_f32_16x16x32_bf16 v[112:115], v[180:183], v[188:191], v[112:115]
	v_mfma_f32_16x16x32_bf16 v[100:103], v[148:151], v[196:199], v[100:103]
	v_mfma_f32_16x16x32_bf16 v[96:99], v[180:183], v[196:199], v[96:99]
	v_mfma_f32_16x16x32_bf16 v[84:87], v[148:151], v[210:213], v[84:87]
	v_mfma_f32_16x16x32_bf16 v[80:83], v[180:183], v[210:213], v[80:83]
	v_mfma_f32_16x16x32_bf16 v[68:71], v[148:151], v[234:237], v[68:71]
	v_mfma_f32_16x16x32_bf16 v[64:67], v[180:183], v[234:237], v[64:67]
	s_setprio 0
	s_barrier
	s_add_i32 s22, s22, s81
	v_lshl_add_u64 v[162:163], v[162:163], 0, s[48:49]
	s_mov_b32 m0, s22
	ds_read_b128 v[184:187], v205 offset:49152
	ds_read_b128 v[188:191], v205 offset:50176
	ds_read_b128 v[192:195], v205 offset:51200
	ds_read_b128 v[196:199], v205 offset:52224
	ds_read_b128 v[206:209], v205 offset:53248
	ds_read_b128 v[210:213], v205 offset:54272
	ds_read_b128 v[222:225], v205 offset:55296
	ds_read_b128 v[234:237], v205 offset:56320
	global_load_lds_dwordx4 v[162:163], off
	v_lshl_add_u64 v[162:163], v[164:165], 0, s[48:49]
	s_add_i32 m0, s22, 0x2000
	s_add_i32 s22, s23, s81
	global_load_lds_dwordx4 v[162:163], off
	v_lshl_add_u64 v[162:163], v[200:201], 0, s[48:49]
	s_mov_b32 m0, s22
	s_nop 0
	global_load_lds_dwordx4 v[162:163], off
	v_lshl_add_u64 v[162:163], v[214:215], 0, s[48:49]
	s_add_i32 m0, s22, 0x2000
	s_nop 0
	global_load_lds_dwordx4 v[162:163], off
	v_lshl_add_u64 v[162:163], v[226:227], 0, s[48:49]
	s_mov_b32 m0, s90
	s_nop 0
	global_load_lds_dwordx4 v[162:163], off
	v_lshl_add_u64 v[162:163], v[238:239], 0, s[48:49]
	s_mov_b32 m0, s91
	s_nop 0
	global_load_lds_dwordx4 v[162:163], off
	s_waitcnt vmcnt(8)
	s_waitcnt lgkmcnt(0)
	s_barrier
	s_setprio 1
	s_waitcnt lgkmcnt(0)
	v_mfma_f32_16x16x32_bf16 v[60:63], v[128:131], v[184:187], v[60:63]
	v_mfma_f32_16x16x32_bf16 v[56:59], v[136:139], v[184:187], v[56:59]
	v_mfma_f32_16x16x32_bf16 v[44:47], v[128:131], v[192:195], v[44:47]
	v_mfma_f32_16x16x32_bf16 v[40:43], v[136:139], v[192:195], v[40:43]
	v_mfma_f32_16x16x32_bf16 v[28:31], v[128:131], v[206:209], v[28:31]
	v_mfma_f32_16x16x32_bf16 v[24:27], v[136:139], v[206:209], v[24:27]
	v_mfma_f32_16x16x32_bf16 v[12:15], v[128:131], v[222:225], v[12:15]
	v_mfma_f32_16x16x32_bf16 v[8:11], v[136:139], v[222:225], v[8:11]
	v_mfma_f32_16x16x32_bf16 v[60:63], v[132:135], v[188:191], v[60:63]
	v_mfma_f32_16x16x32_bf16 v[56:59], v[140:143], v[188:191], v[56:59]
	v_mfma_f32_16x16x32_bf16 v[44:47], v[132:135], v[196:199], v[44:47]
	v_mfma_f32_16x16x32_bf16 v[40:43], v[140:143], v[196:199], v[40:43]
	v_mfma_f32_16x16x32_bf16 v[28:31], v[132:135], v[210:213], v[28:31]
	v_mfma_f32_16x16x32_bf16 v[24:27], v[140:143], v[210:213], v[24:27]
	v_mfma_f32_16x16x32_bf16 v[12:15], v[132:135], v[234:237], v[12:15]
	v_mfma_f32_16x16x32_bf16 v[8:11], v[140:143], v[234:237], v[8:11]
	v_mfma_f32_16x16x32_bf16 v[52:55], v[144:147], v[184:187], v[52:55]
	v_mfma_f32_16x16x32_bf16 v[48:51], v[152:155], v[184:187], v[48:51]
	v_mfma_f32_16x16x32_bf16 v[36:39], v[144:147], v[192:195], v[36:39]
	v_mfma_f32_16x16x32_bf16 v[32:35], v[152:155], v[192:195], v[32:35]
	v_mfma_f32_16x16x32_bf16 v[20:23], v[144:147], v[206:209], v[20:23]
	v_mfma_f32_16x16x32_bf16 v[16:19], v[152:155], v[206:209], v[16:19]
	v_mfma_f32_16x16x32_bf16 v[4:7], v[144:147], v[222:225], v[4:7]
	v_mfma_f32_16x16x32_bf16 v[0:3], v[152:155], v[222:225], v[0:3]
	v_mfma_f32_16x16x32_bf16 v[52:55], v[148:151], v[188:191], v[52:55]
	v_mfma_f32_16x16x32_bf16 v[48:51], v[180:183], v[188:191], v[48:51]
	v_mfma_f32_16x16x32_bf16 v[36:39], v[148:151], v[196:199], v[36:39]
	v_mfma_f32_16x16x32_bf16 v[32:35], v[180:183], v[196:199], v[32:35]
	v_mfma_f32_16x16x32_bf16 v[20:23], v[148:151], v[210:213], v[20:23]
	v_mfma_f32_16x16x32_bf16 v[16:19], v[180:183], v[210:213], v[16:19]
	v_mfma_f32_16x16x32_bf16 v[4:7], v[148:151], v[234:237], v[4:7]
	v_mfma_f32_16x16x32_bf16 v[0:3], v[180:183], v[234:237], v[0:3]
	s_setprio 0
	s_barrier
	s_add_u32 s40, s40, 0x100
	s_addc_u32 s41, s41, 0
	s_add_u32 s4, s4, 0x100
	s_addc_u32 s84, s84, 0
	s_cmp_ge_u32 s85, s94
	s_mov_b32 s82, s85
	.p2align 6

.LBB0_477:
	s_ashr_i32 s17, s16, 31
	s_lshl_b64 s[18:19], s[16:17], 19
	s_add_u32 s18, s0, s18
	s_addc_u32 s19, s1, s19
	s_and_b64 s[24:25], s[38:39], exec
	s_cselect_b32 s4, s19, s41
	s_cselect_b32 s9, s18, s40
	s_ashr_i32 s85, s84, 31
	s_lshl_b64 s[24:25], s[84:85], 19
	s_add_u32 s82, s80, s24
	s_addc_u32 s83, s81, s25
	s_and_b64 s[24:25], s[38:39], exec
	s_cselect_b32 s17, s83, s13
	s_cselect_b32 s24, s82, s12
	s_add_u32 s40, s40, 0x40080
	s_addc_u32 s41, s41, 0
	s_add_u32 s25, s12, 0x100
	s_addc_u32 s50, s13, 0
	s_mov_b32 s51, -2
	s_add_u32 s12, s40, 0xfffc0080
	s_addc_u32 s13, s41, -1
	s_add_i32 s85, 0, 0x10000
	s_cmp_eq_u32 s51, 12
	s_cselect_b32 s43, s4, s13
	s_cselect_b32 s42, s9, s12
	v_add_u32_e32 v158, s85, v196
	s_cselect_b32 s13, s17, s50
	s_cselect_b32 s12, s24, s25
	s_add_i32 s27, 0, 0x14000
	ds_read_b128 v[150:153], v158
	ds_read_b128 v[154:157], v158 offset:1024
	ds_read_b128 v[170:173], v158 offset:2048
	ds_read_b128 v[174:177], v158 offset:3072
	v_add_u32_e32 v158, s27, v196
	ds_read_b128 v[178:181], v158
	ds_read_b128 v[182:185], v158 offset:1024
	ds_read_b128 v[186:189], v158 offset:2048
	ds_read_b128 v[200:203], v158 offset:3072
	s_add_i32 m0, s15, 0xc000
	ds_read_b128 v[204:207], v199
	ds_read_b128 v[208:211], v199 offset:1024
	ds_read_b128 v[212:215], v199 offset:2048
	ds_read_b128 v[234:237], v199 offset:3072
	ds_read_b128 v[238:241], v199 offset:4096
	ds_read_b128 v[242:245], v199 offset:5120
	ds_read_b128 v[246:249], v199 offset:6144
	ds_read_b128 v[222:225], v199 offset:7168
	global_load_lds_dwordx4 v146, s[40:41]
	s_add_i32 m0, s15, 0xe000
	s_nop 0
	global_load_lds_dwordx4 v148, s[40:41]
	s_waitcnt vmcnt(8)
	s_waitcnt lgkmcnt(0)
	s_barrier
	s_setprio 1
	s_waitcnt lgkmcnt(0)
	v_mfma_f32_16x16x32_bf16 v[124:127], v[150:153], v[204:207], 0
	v_mfma_f32_16x16x32_bf16 v[120:123], v[170:173], v[204:207], 0
	v_mfma_f32_16x16x32_bf16 v[108:111], v[150:153], v[212:215], 0
	v_mfma_f32_16x16x32_bf16 v[104:107], v[170:173], v[212:215], 0
	v_mfma_f32_16x16x32_bf16 v[92:95], v[150:153], v[238:241], 0
	v_mfma_f32_16x16x32_bf16 v[88:91], v[170:173], v[238:241], 0
	v_mfma_f32_16x16x32_bf16 v[76:79], v[150:153], v[246:249], 0
	v_mfma_f32_16x16x32_bf16 v[72:75], v[170:173], v[246:249], 0
	v_mfma_f32_16x16x32_bf16 v[124:127], v[154:157], v[208:211], v[124:127]
	v_mfma_f32_16x16x32_bf16 v[120:123], v[174:177], v[208:211], v[120:123]
	v_mfma_f32_16x16x32_bf16 v[108:111], v[154:157], v[234:237], v[108:111]
	v_mfma_f32_16x16x32_bf16 v[104:107], v[174:177], v[234:237], v[104:107]
	v_mfma_f32_16x16x32_bf16 v[92:95], v[154:157], v[242:245], v[92:95]
	v_mfma_f32_16x16x32_bf16 v[88:91], v[174:177], v[242:245], v[88:91]
	v_mfma_f32_16x16x32_bf16 v[76:79], v[154:157], v[222:225], v[76:79]
	v_mfma_f32_16x16x32_bf16 v[72:75], v[174:177], v[222:225], v[72:75]
	v_mfma_f32_16x16x32_bf16 v[116:119], v[178:181], v[204:207], 0
	v_mfma_f32_16x16x32_bf16 v[112:115], v[186:189], v[204:207], 0
	v_mfma_f32_16x16x32_bf16 v[100:103], v[178:181], v[212:215], 0
	v_mfma_f32_16x16x32_bf16 v[96:99], v[186:189], v[212:215], 0
	v_mfma_f32_16x16x32_bf16 v[84:87], v[178:181], v[238:241], 0
	v_mfma_f32_16x16x32_bf16 v[80:83], v[186:189], v[238:241], 0
	v_mfma_f32_16x16x32_bf16 v[68:71], v[178:181], v[246:249], 0
	v_mfma_f32_16x16x32_bf16 v[64:67], v[186:189], v[246:249], 0
	v_mfma_f32_16x16x32_bf16 v[116:119], v[182:185], v[208:211], v[116:119]
	v_mfma_f32_16x16x32_bf16 v[112:115], v[200:203], v[208:211], v[112:115]
	v_mfma_f32_16x16x32_bf16 v[100:103], v[182:185], v[234:237], v[100:103]
	v_mfma_f32_16x16x32_bf16 v[96:99], v[200:203], v[234:237], v[96:99]
	v_mfma_f32_16x16x32_bf16 v[84:87], v[182:185], v[242:245], v[84:87]
	v_mfma_f32_16x16x32_bf16 v[80:83], v[200:203], v[242:245], v[80:83]
	v_mfma_f32_16x16x32_bf16 v[68:71], v[182:185], v[222:225], v[68:71]
	v_mfma_f32_16x16x32_bf16 v[64:67], v[200:203], v[222:225], v[64:67]
	s_setprio 0
	s_barrier
	s_add_i32 s85, s85, s86
	s_mov_b32 m0, s85
	ds_read_b128 v[204:207], v199 offset:16384
	ds_read_b128 v[208:211], v199 offset:17408
	ds_read_b128 v[212:215], v199 offset:18432
	ds_read_b128 v[222:225], v199 offset:19456
	ds_read_b128 v[234:237], v199 offset:20480
	ds_read_b128 v[238:241], v199 offset:21504
	ds_read_b128 v[242:245], v199 offset:22528
	ds_read_b128 v[246:249], v199 offset:23552
	global_load_lds_dwordx4 v130, s[12:13]
	s_add_i32 m0, s85, 0x2000
	s_add_u32 s98, s12, 0x40000
	s_addc_u32 s99, s13, 0
	s_add_i32 s27, s27, s86
	global_load_lds_dwordx4 v134, s[12:13]
	s_mov_b32 m0, s27
	s_nop 0
	global_load_lds_dwordx4 v130, s[98:99]
	s_add_i32 m0, s27, 0x2000
	s_nop 0
	global_load_lds_dwordx4 v134, s[98:99]
	s_mov_b32 m0, s15
	s_nop 0
	global_load_lds_dwordx4 v128, s[42:43]
	s_mov_b32 m0, s87
	s_nop 0
	global_load_lds_dwordx4 v132, s[42:43]
	s_waitcnt vmcnt(8)
	s_waitcnt lgkmcnt(0)
	s_barrier
	s_setprio 1
	s_waitcnt lgkmcnt(0)
	v_mfma_f32_16x16x32_bf16 v[60:63], v[150:153], v[204:207], 0
	v_mfma_f32_16x16x32_bf16 v[56:59], v[170:173], v[204:207], 0
	v_mfma_f32_16x16x32_bf16 v[44:47], v[150:153], v[212:215], 0
	v_mfma_f32_16x16x32_bf16 v[40:43], v[170:173], v[212:215], 0
	v_mfma_f32_16x16x32_bf16 v[28:31], v[150:153], v[234:237], 0
	v_mfma_f32_16x16x32_bf16 v[24:27], v[170:173], v[234:237], 0
	v_mfma_f32_16x16x32_bf16 v[12:15], v[150:153], v[242:245], 0
	v_mfma_f32_16x16x32_bf16 v[8:11], v[170:173], v[242:245], 0
	v_mfma_f32_16x16x32_bf16 v[60:63], v[154:157], v[208:211], v[60:63]
	v_mfma_f32_16x16x32_bf16 v[56:59], v[174:177], v[208:211], v[56:59]
	v_mfma_f32_16x16x32_bf16 v[44:47], v[154:157], v[222:225], v[44:47]
	v_mfma_f32_16x16x32_bf16 v[40:43], v[174:177], v[222:225], v[40:43]
	v_mfma_f32_16x16x32_bf16 v[28:31], v[154:157], v[238:241], v[28:31]
	v_mfma_f32_16x16x32_bf16 v[24:27], v[174:177], v[238:241], v[24:27]
	v_mfma_f32_16x16x32_bf16 v[12:15], v[154:157], v[246:249], v[12:15]
	v_mfma_f32_16x16x32_bf16 v[8:11], v[174:177], v[246:249], v[8:11]
	v_mfma_f32_16x16x32_bf16 v[52:55], v[178:181], v[204:207], 0
	v_mfma_f32_16x16x32_bf16 v[48:51], v[186:189], v[204:207], 0
	v_mfma_f32_16x16x32_bf16 v[36:39], v[178:181], v[212:215], 0
	v_mfma_f32_16x16x32_bf16 v[32:35], v[186:189], v[212:215], 0
	v_mfma_f32_16x16x32_bf16 v[20:23], v[178:181], v[234:237], 0
	v_mfma_f32_16x16x32_bf16 v[16:19], v[186:189], v[234:237], 0
	v_mfma_f32_16x16x32_bf16 v[4:7], v[178:181], v[242:245], 0
	v_mfma_f32_16x16x32_bf16 v[0:3], v[186:189], v[242:245], 0
	v_mfma_f32_16x16x32_bf16 v[52:55], v[182:185], v[208:211], v[52:55]
	v_mfma_f32_16x16x32_bf16 v[48:51], v[200:203], v[208:211], v[48:51]
	v_mfma_f32_16x16x32_bf16 v[36:39], v[182:185], v[222:225], v[36:39]
	v_mfma_f32_16x16x32_bf16 v[32:35], v[200:203], v[222:225], v[32:35]
	v_mfma_f32_16x16x32_bf16 v[20:23], v[182:185], v[238:241], v[20:23]
	v_mfma_f32_16x16x32_bf16 v[16:19], v[200:203], v[238:241], v[16:19]
	v_mfma_f32_16x16x32_bf16 v[4:7], v[182:185], v[246:249], v[4:7]
	v_mfma_f32_16x16x32_bf16 v[0:3], v[200:203], v[246:249], v[0:3]
	s_setprio 0
	s_barrier
	s_add_i32 s27, 0, 0x18000
	v_add_u32_e32 v160, s27, v196
	s_add_i32 s85, 0, 0x1c000
	ds_read_b128 v[150:153], v160
	ds_read_b128 v[154:157], v160 offset:1024
	ds_read_b128 v[170:173], v160 offset:2048
	ds_read_b128 v[174:177], v160 offset:3072
	v_add_u32_e32 v160, s85, v196
	ds_read_b128 v[178:181], v160
	ds_read_b128 v[182:185], v160 offset:1024
	ds_read_b128 v[186:189], v160 offset:2048
	ds_read_b128 v[200:203], v160 offset:3072
	s_add_u32 s42, s42, 0x40000
	s_addc_u32 s43, s43, 0
	s_mov_b32 m0, s88
	ds_read_b128 v[204:207], v199 offset:32768
	ds_read_b128 v[208:211], v199 offset:33792
	ds_read_b128 v[212:215], v199 offset:34816
	ds_read_b128 v[222:225], v199 offset:35840
	ds_read_b128 v[234:237], v199 offset:36864
	ds_read_b128 v[238:241], v199 offset:37888
	ds_read_b128 v[242:245], v199 offset:38912
	ds_read_b128 v[246:249], v199 offset:39936
	global_load_lds_dwordx4 v128, s[42:43]
	s_mov_b32 m0, s89
	s_nop 0
	global_load_lds_dwordx4 v132, s[42:43]
	s_waitcnt vmcnt(8)
	s_waitcnt lgkmcnt(0)
	s_barrier
	s_setprio 1
	s_waitcnt lgkmcnt(0)
	v_mfma_f32_16x16x32_bf16 v[124:127], v[150:153], v[204:207], v[124:127]
	v_mfma_f32_16x16x32_bf16 v[120:123], v[170:173], v[204:207], v[120:123]
	v_mfma_f32_16x16x32_bf16 v[108:111], v[150:153], v[212:215], v[108:111]
	v_mfma_f32_16x16x32_bf16 v[104:107], v[170:173], v[212:215], v[104:107]
	v_mfma_f32_16x16x32_bf16 v[92:95], v[150:153], v[234:237], v[92:95]
	v_mfma_f32_16x16x32_bf16 v[88:91], v[170:173], v[234:237], v[88:91]
	v_mfma_f32_16x16x32_bf16 v[76:79], v[150:153], v[242:245], v[76:79]
	v_mfma_f32_16x16x32_bf16 v[72:75], v[170:173], v[242:245], v[72:75]
	v_mfma_f32_16x16x32_bf16 v[124:127], v[154:157], v[208:211], v[124:127]
	v_mfma_f32_16x16x32_bf16 v[120:123], v[174:177], v[208:211], v[120:123]
	v_mfma_f32_16x16x32_bf16 v[108:111], v[154:157], v[222:225], v[108:111]
	v_mfma_f32_16x16x32_bf16 v[104:107], v[174:177], v[222:225], v[104:107]
	v_mfma_f32_16x16x32_bf16 v[92:95], v[154:157], v[238:241], v[92:95]
	v_mfma_f32_16x16x32_bf16 v[88:91], v[174:177], v[238:241], v[88:91]
	v_mfma_f32_16x16x32_bf16 v[76:79], v[154:157], v[246:249], v[76:79]
	v_mfma_f32_16x16x32_bf16 v[72:75], v[174:177], v[246:249], v[72:75]
	v_mfma_f32_16x16x32_bf16 v[116:119], v[178:181], v[204:207], v[116:119]
	v_mfma_f32_16x16x32_bf16 v[112:115], v[186:189], v[204:207], v[112:115]
	v_mfma_f32_16x16x32_bf16 v[100:103], v[178:181], v[212:215], v[100:103]
	v_mfma_f32_16x16x32_bf16 v[96:99], v[186:189], v[212:215], v[96:99]
	v_mfma_f32_16x16x32_bf16 v[84:87], v[178:181], v[234:237], v[84:87]
	v_mfma_f32_16x16x32_bf16 v[80:83], v[186:189], v[234:237], v[80:83]
	v_mfma_f32_16x16x32_bf16 v[68:71], v[178:181], v[242:245], v[68:71]
	v_mfma_f32_16x16x32_bf16 v[64:67], v[186:189], v[242:245], v[64:67]
	v_mfma_f32_16x16x32_bf16 v[116:119], v[182:185], v[208:211], v[116:119]
	v_mfma_f32_16x16x32_bf16 v[112:115], v[200:203], v[208:211], v[112:115]
	v_mfma_f32_16x16x32_bf16 v[100:103], v[182:185], v[222:225], v[100:103]
	v_mfma_f32_16x16x32_bf16 v[96:99], v[200:203], v[222:225], v[96:99]
	v_mfma_f32_16x16x32_bf16 v[84:87], v[182:185], v[238:241], v[84:87]
	v_mfma_f32_16x16x32_bf16 v[80:83], v[200:203], v[238:241], v[80:83]
	v_mfma_f32_16x16x32_bf16 v[68:71], v[182:185], v[246:249], v[68:71]
	v_mfma_f32_16x16x32_bf16 v[64:67], v[200:203], v[246:249], v[64:67]
	s_setprio 0
	s_barrier
	s_add_i32 s27, s27, s86
	s_add_u32 s100, s12, 0x80
	s_addc_u32 s101, s13, 0
	s_mov_b32 m0, s27
	ds_read_b128 v[204:207], v199 offset:49152
	ds_read_b128 v[208:211], v199 offset:50176
	ds_read_b128 v[212:215], v199 offset:51200
	ds_read_b128 v[222:225], v199 offset:52224
	ds_read_b128 v[234:237], v199 offset:53248
	ds_read_b128 v[238:241], v199 offset:54272
	ds_read_b128 v[242:245], v199 offset:55296
	ds_read_b128 v[246:249], v199 offset:56320
	global_load_lds_dwordx4 v130, s[100:101]
	s_add_i32 m0, s27, 0x2000
	s_add_u32 s12, s12, 0x40080
	s_addc_u32 s13, s13, 0
	s_add_i32 s27, s85, s86
	global_load_lds_dwordx4 v134, s[100:101]
	s_mov_b32 m0, s27
	s_nop 0
	global_load_lds_dwordx4 v130, s[12:13]
	s_add_i32 m0, s27, 0x2000
	s_nop 0
	global_load_lds_dwordx4 v134, s[12:13]
	s_add_u32 s98, s42, 0xfffc0080
	s_addc_u32 s99, s43, -1
	s_mov_b32 m0, s92
	s_nop 0
	global_load_lds_dwordx4 v128, s[98:99]
	s_mov_b32 m0, s93
	s_nop 0
	global_load_lds_dwordx4 v132, s[98:99]
	s_waitcnt vmcnt(8)
	s_waitcnt lgkmcnt(0)
	s_barrier
	s_setprio 1
	s_waitcnt lgkmcnt(0)
	v_mfma_f32_16x16x32_bf16 v[60:63], v[150:153], v[204:207], v[60:63]
	v_mfma_f32_16x16x32_bf16 v[56:59], v[170:173], v[204:207], v[56:59]
	v_mfma_f32_16x16x32_bf16 v[44:47], v[150:153], v[212:215], v[44:47]
	v_mfma_f32_16x16x32_bf16 v[40:43], v[170:173], v[212:215], v[40:43]
	v_mfma_f32_16x16x32_bf16 v[28:31], v[150:153], v[234:237], v[28:31]
	v_mfma_f32_16x16x32_bf16 v[24:27], v[170:173], v[234:237], v[24:27]
	v_mfma_f32_16x16x32_bf16 v[12:15], v[150:153], v[242:245], v[12:15]
	v_mfma_f32_16x16x32_bf16 v[8:11], v[170:173], v[242:245], v[8:11]
	v_mfma_f32_16x16x32_bf16 v[60:63], v[154:157], v[208:211], v[60:63]
	v_mfma_f32_16x16x32_bf16 v[56:59], v[174:177], v[208:211], v[56:59]
	v_mfma_f32_16x16x32_bf16 v[44:47], v[154:157], v[222:225], v[44:47]
	v_mfma_f32_16x16x32_bf16 v[40:43], v[174:177], v[222:225], v[40:43]
	v_mfma_f32_16x16x32_bf16 v[28:31], v[154:157], v[238:241], v[28:31]
	v_mfma_f32_16x16x32_bf16 v[24:27], v[174:177], v[238:241], v[24:27]
	v_mfma_f32_16x16x32_bf16 v[12:15], v[154:157], v[246:249], v[12:15]
	v_mfma_f32_16x16x32_bf16 v[8:11], v[174:177], v[246:249], v[8:11]
	v_mfma_f32_16x16x32_bf16 v[52:55], v[178:181], v[204:207], v[52:55]
	v_mfma_f32_16x16x32_bf16 v[48:51], v[186:189], v[204:207], v[48:51]
	v_mfma_f32_16x16x32_bf16 v[36:39], v[178:181], v[212:215], v[36:39]
	v_mfma_f32_16x16x32_bf16 v[32:35], v[186:189], v[212:215], v[32:35]
	v_mfma_f32_16x16x32_bf16 v[20:23], v[178:181], v[234:237], v[20:23]
	v_mfma_f32_16x16x32_bf16 v[16:19], v[186:189], v[234:237], v[16:19]
	v_mfma_f32_16x16x32_bf16 v[4:7], v[178:181], v[242:245], v[4:7]
	v_mfma_f32_16x16x32_bf16 v[0:3], v[186:189], v[242:245], v[0:3]
	v_mfma_f32_16x16x32_bf16 v[52:55], v[182:185], v[208:211], v[52:55]
	v_mfma_f32_16x16x32_bf16 v[48:51], v[200:203], v[208:211], v[48:51]
	v_mfma_f32_16x16x32_bf16 v[36:39], v[182:185], v[222:225], v[36:39]
	v_mfma_f32_16x16x32_bf16 v[32:35], v[200:203], v[222:225], v[32:35]
	v_mfma_f32_16x16x32_bf16 v[20:23], v[182:185], v[238:241], v[20:23]
	v_mfma_f32_16x16x32_bf16 v[16:19], v[200:203], v[238:241], v[16:19]
	v_mfma_f32_16x16x32_bf16 v[4:7], v[182:185], v[246:249], v[4:7]
	v_mfma_f32_16x16x32_bf16 v[0:3], v[200:203], v[246:249], v[0:3]
	s_setprio 0
	s_barrier
	s_add_i32 s51, s51, 2
	s_add_u32 s40, s40, 0x100
	s_addc_u32 s41, s41, 0
	s_add_u32 s25, s25, 0x100
	s_addc_u32 s50, s50, 0
	s_cmp_gt_u32 s51, 13
	.p2align 6
